# norm row loop: next-row prefetch into spare VGPRs (loads issued before reduce/normalize/route), copy at loop top
# baseline (speedup 1.0000x reference)
; __device__ __forceinline__ void norm_phase(const Params& P, LAS unsigned char* lds, int layer, int which, int nrows, int flags, int fprev, int fnext, const float* g2ovr, const float* xsrc, const float* gcp) {
;     ...
;         int2 nsr = make_int2(0, 0); float2 nw = make_float2(0.f, 0.f);
;         if ((flags & 4) && rlo + gw < rhi) { nsr = ((const int2*)(ws + O_SROW))[rlo + gw]; nw = rw[rlo + gw]; }
;         for (int r = rlo + gw; r < rhi; r += ngw) {
;             f32x4 v[4];
;             const f32x4* xr = (const f32x4*)((r < SEQ ? xsrc : xres) + (size_t)r * D) + lane;
; #pragma unroll
;             for (int j = 0; j < 4; ++j) v[j] = xr[64 * j];
.LBB0_1198:
	v_ashrrev_i32_e32 v67, 31, v66
	v_lshlrev_b64 v[120:121], 12, v[66:67]
	v_lshlrev_b32_e32 v135, 7, v66
	v_lshlrev_b64 v[118:119], 3, v[66:67]
	v_or_b32_e32 v120, v102, v120
	s_mov_b64 s[72:73], 0
	v_readlane_b32 s100, v253, 34
	v_readlane_b32 s101, v253, 35
	v_cmp_gt_i32_e32 vcc, s33, v66
	s_nop 1
	s_and_b64 vcc, s[100:101], vcc
	v_readlane_b32 s100, v252, 36
	v_readlane_b32 s101, v252, 37
	v_mov_b32_e32 v178, s22
	v_mov_b32_e32 v179, s23
	s_nop 0
	v_mov_b32_e32 v177, s101
	v_cndmask_b32_e32 v179, v179, v177, vcc
	v_mov_b32_e32 v177, s100
	v_cndmask_b32_e32 v178, v178, v177, vcc
	v_lshl_add_u64 v[178:179], v[178:179], 0, v[120:121]
	global_load_dwordx4 v[160:163], v[178:179], off
	global_load_dwordx4 v[164:167], v[178:179], off offset:1024
	global_load_dwordx4 v[168:171], v[178:179], off offset:2048
	global_load_dwordx4 v[172:175], v[178:179], off offset:3072
	s_waitcnt vmcnt(0)
	s_branch .LBB0_1201

; __device__ __forceinline__ void norm_phase(const Params& P, LAS unsigned char* lds, int layer, int which, int nrows, int flags, int fprev, int fnext, const float* g2ovr, const float* xsrc, const float* gcp) {
;     ...
;         for (int r = rlo + gw; r < rhi; r += ngw) {
;             f32x4 v[4];
;             const f32x4* xr = (const f32x4*)((r < SEQ ? xsrc : xres) + (size_t)r * D) + lane;
; #pragma unroll
;             for (int j = 0; j < 4; ++j) v[j] = xr[64 * j];
.LBB0_1201:
	v_add_u32_e32 v136, s66, v98
	v_readlane_b32 s80, v252, 36
	v_readlane_b32 s2, v253, 34
	v_cmp_gt_i32_e64 s[4:5], s33, v136
	v_readlane_b32 s81, v252, 37
	v_readlane_b32 s3, v253, 35
	v_mov_b32_e32 v0, s23
	v_mov_b32_e32 v50, s81
	s_and_b64 vcc, s[2:3], s[4:5]
	v_cndmask_b32_e32 v51, v0, v50, vcc
	v_mov_b32_e32 v0, s22
	v_mov_b32_e32 v50, s80
	v_cndmask_b32_e32 v50, v0, v50, vcc
	v_lshl_add_u64 v[50:51], v[50:51], 0, v[120:121]
	s_waitcnt lgkmcnt(0)
	s_and_b64 vcc, exec, s[10:11]
	s_cbranch_vccnz .Lnp_orig
	s_waitcnt vmcnt(4)
	v_mov_b64_e32 v[62:63], v[160:161]
	v_mov_b64_e32 v[64:65], v[162:163]
	v_mov_b64_e32 v[58:59], v[164:165]
	v_mov_b64_e32 v[60:61], v[166:167]
	v_mov_b64_e32 v[54:55], v[168:169]
	v_mov_b64_e32 v[56:57], v[170:171]
	v_mov_b64_e32 v[50:51], v[172:173]
	v_mov_b64_e32 v[52:53], v[174:175]
	s_branch .Lnp_join
.Lnp_orig:
	global_load_dwordx4 v[62:65], v[50:51], off
	global_load_dwordx4 v[58:61], v[50:51], off offset:1024
	global_load_dwordx4 v[54:57], v[50:51], off offset:2048
	s_nop 0
	global_load_dwordx4 v[50:53], v[50:51], off offset:3072
.Lnp_join:
	s_andn2_b64 vcc, exec, s[42:43]
	v_readlane_b32 s82, v252, 38
	v_readlane_b32 s83, v252, 39
	v_readlane_b32 s84, v252, 40
	v_readlane_b32 s85, v252, 41
	v_readlane_b32 s86, v252, 42
	v_readlane_b32 s87, v252, 43
	v_readlane_b32 s88, v252, 44
	v_readlane_b32 s89, v252, 45
	v_readlane_b32 s90, v252, 46
	v_readlane_b32 s91, v252, 47
	v_readlane_b32 s92, v252, 48
	v_readlane_b32 s93, v252, 49
	v_readlane_b32 s94, v252, 50
	v_readlane_b32 s95, v252, 51
	s_cbranch_vccnz .LBB0_1214
	v_add_u32_e32 v66, s66, v103
	v_cmp_gt_i32_e32 vcc, s68, v66
	v_mov_b64_e32 v[122:123], v[116:117]
	v_mov_b64_e32 v[124:125], v[74:75]
	s_and_saveexec_b64 s[6:7], vcc
	s_cbranch_execz .LBB0_1204
	v_ashrrev_i32_e32 v67, 31, v66
	v_readlane_b32 s2, v250, 25
	v_lshlrev_b64 v[66:67], 3, v[66:67]
	v_readlane_b32 s3, v250, 26
	s_nop 1
	v_lshl_add_u64 v[68:69], s[2:3], 0, v[66:67]
	v_lshl_add_u64 v[66:67], s[60:61], 0, v[66:67]
	global_load_dwordx2 v[124:125], v[68:69], off
	global_load_dwordx2 v[122:123], v[66:67], off

; __device__ __forceinline__ unsigned pk2(float lo, float hi) { unsigned r; asm("v_cvt_pk_bf16_f32 %0, %1, %2" : "=v"(r) : "v"(lo), "v"(hi)); return r; }
; __device__ __forceinline__ void norm_phase(const Params& P, LAS unsigned char* lds, int layer, int which, int nrows, int flags, int fprev, int fnext, const float* g2ovr, const float* xsrc, const float* gcp) {
;     ...
;         for (int r = rlo + gw; r < rhi; r += ngw) {
;             f32x4 v[4];
;             const f32x4* xr = (const f32x4*)((r < SEQ ? xsrc : xres) + (size_t)r * D) + lane;
; #pragma unroll
;             for (int j = 0; j < 4; ++j) v[j] = xr[64 * j];
;     ...
;             if (flags & 8) continue;
;             float ss = 0.f;
; #pragma unroll
;             for (int j = 0; j < 4; ++j) ss += (v[j][0] * v[j][0] + v[j][1] * v[j][1]) + (v[j][2] * v[j][2] + v[j][3] * v[j][3]);
;             const float rstd = rsqrtf(wave_sum(ss) * (1.f / D) + 1e-6f);
; #pragma unroll
;             for (int j = 0; j < 4; ++j) v[j] = v[j] * rstd * ga[j] + sh[j];
;             int orow = r;
;             if ((flags & 1) && r < SEQ) orow = 128 * (r & 127) + (r >> 7);
;             u32x2* o8 = (u32x2*)(hbuf + (size_t)orow * D) + lane;
; #pragma unroll
;             for (int j = 0; j < 4; ++j) { u32x2 o; o.x = pk2(v[j][0], v[j][1]); o.y = pk2(v[j][2], v[j][3]); o8[64 * j] = o; }
.LBB0_1240:
	v_add_u32_e32 v176, s38, v136
	v_readlane_b32 s100, v253, 34
	v_readlane_b32 s101, v253, 35
	v_cmp_gt_i32_e32 vcc, s33, v176
	s_nop 1
	s_and_b64 vcc, s[100:101], vcc
	v_readlane_b32 s100, v252, 36
	v_readlane_b32 s101, v252, 37
	v_mov_b32_e32 v178, s22
	v_mov_b32_e32 v179, s23
	s_nop 0
	v_mov_b32_e32 v177, s101
	v_cndmask_b32_e32 v179, v179, v177, vcc
	v_mov_b32_e32 v177, s100
	v_cndmask_b32_e32 v178, v178, v177, vcc
	v_lshl_add_u64 v[178:179], v[178:179], 0, v[120:121]
	v_lshl_add_u64 v[178:179], v[178:179], 0, s[34:35]
	v_cmp_gt_i32_e32 vcc, s68, v176
	s_and_saveexec_b64 s[100:101], vcc
	global_load_dwordx4 v[160:163], v[178:179], off
	global_load_dwordx4 v[164:167], v[178:179], off offset:1024
	global_load_dwordx4 v[168:171], v[178:179], off offset:2048
	global_load_dwordx4 v[172:175], v[178:179], off offset:3072
	s_or_b64 exec, exec, s[100:101]
	v_pk_mul_f32 v[70:71], v[64:65], v[64:65]
	v_pk_mul_f32 v[72:73], v[62:63], v[62:63]
	v_pk_mul_f32 v[66:67], v[60:61], v[60:61]
	v_pk_mul_f32 v[68:69], v[58:59], v[58:59]
	v_pk_mov_b32 v[76:77], v[72:73], v[70:71] op_sel:[1,0]
	v_mov_b32_e32 v73, v71
	v_pk_add_f32 v[70:71], v[76:77], v[72:73]
	v_pk_mov_b32 v[72:73], v[68:69], v[66:67] op_sel:[1,0]
	v_mov_b32_e32 v69, v67
	v_pk_add_f32 v[66:67], v[72:73], v[68:69]
	v_mul_f32_e32 v0, v54, v54
	v_pk_add_f32 v[70:71], v[70:71], v[70:71] op_sel_hi:[0,1]
	v_pk_add_f32 v[66:67], v[66:67], v[66:67] op_sel_hi:[0,1]
	v_pk_fma_f32 v[68:69], v[54:55], v[54:55], v[0:1] op_sel_hi:[1,1,0]
	v_mul_f32_e32 v0, v56, v56
	v_pk_fma_f32 v[72:73], v[56:57], v[56:57], v[0:1] op_sel_hi:[1,1,0]
	v_mul_f32_e32 v70, v52, v52
	v_mul_f32_e32 v66, v53, v53
	v_and_b32_e32 v0, 64, v209
	v_mul_f32_e32 v68, v50, v50
	v_mul_f32_e32 v72, v51, v51
	v_pk_add_f32 v[66:67], v[70:71], v[66:67]
	v_add_u32_e32 v70, 64, v0
	v_xor_b32_e32 v0, 1, v209
	v_pk_add_f32 v[68:69], v[68:69], v[72:73]
	v_cmp_lt_i32_e32 vcc, v0, v70
	v_pk_add_f32 v[66:67], v[68:69], v[66:67]
	s_mov_b32 s2, 0x800000
	v_cndmask_b32_e32 v0, v209, v0, vcc
	v_add_f32_e32 v66, v66, v67
	v_lshlrev_b32_e32 v0, 2, v0
	ds_bpermute_b32 v67, v0, v66
	s_waitcnt lgkmcnt(0)
	v_add_f32_e32 v67, v66, v67
	v_xor_b32_e32 v66, 2, v209
	v_cmp_lt_i32_e32 vcc, v66, v70
	s_nop 1
	v_cndmask_b32_e32 v66, v209, v66, vcc
	v_lshlrev_b32_e32 v66, 2, v66
	ds_bpermute_b32 v68, v66, v67
	s_waitcnt lgkmcnt(0)
	v_add_f32_e32 v68, v67, v68
	v_xor_b32_e32 v67, 4, v209
	v_cmp_lt_i32_e32 vcc, v67, v70
	s_nop 1
	v_cndmask_b32_e32 v67, v209, v67, vcc
	v_lshlrev_b32_e32 v67, 2, v67
	ds_bpermute_b32 v69, v67, v68
	s_waitcnt lgkmcnt(0)
	v_add_f32_e32 v69, v68, v69
	v_xor_b32_e32 v68, 8, v209
	v_cmp_lt_i32_e32 vcc, v68, v70
	s_nop 1
	v_cndmask_b32_e32 v68, v209, v68, vcc
	v_lshlrev_b32_e32 v68, 2, v68
	ds_bpermute_b32 v71, v68, v69
	s_waitcnt lgkmcnt(0)
	v_add_f32_e32 v71, v69, v71
	v_xor_b32_e32 v69, 16, v209
	v_cmp_lt_i32_e32 vcc, v69, v70
	s_nop 1
	v_cndmask_b32_e32 v69, v209, v69, vcc
	v_lshlrev_b32_e32 v69, 2, v69
	ds_bpermute_b32 v72, v69, v71
	s_waitcnt lgkmcnt(0)
	v_add_f32_e32 v71, v71, v72
	v_xor_b32_e32 v72, 32, v209
	v_cmp_lt_i32_e32 vcc, v72, v70
	s_nop 1
	v_cndmask_b32_e32 v70, v209, v72, vcc
	v_lshlrev_b32_e32 v70, 2, v70
	ds_bpermute_b32 v72, v70, v71
	s_waitcnt lgkmcnt(0)
	v_add_f32_e32 v71, v71, v72
	v_fmamk_f32 v71, v71, 0x3a800000, v197
	v_mul_f32_e32 v72, 0x4b800000, v71
	v_cmp_gt_f32_e32 vcc, s2, v71
	s_nop 1
	v_cndmask_b32_e32 v71, v71, v72, vcc
	v_rsq_f32_e32 v71, v71
	s_nop 0
	v_mul_f32_e32 v72, 0x45800000, v71
	v_cndmask_b32_e32 v72, v71, v72, vcc
	v_pk_mul_f32 v[76:77], v[62:63], v[72:73] op_sel_hi:[1,0]
	v_pk_mul_f32 v[62:63], v[64:65], v[72:73] op_sel_hi:[1,0]
	v_pk_fma_f32 v[64:65], v[18:19], v[76:77], v[10:11]
	v_pk_mul_f32 v[76:77], v[58:59], v[72:73] op_sel_hi:[1,0]
	v_pk_mul_f32 v[58:59], v[60:61], v[72:73] op_sel_hi:[1,0]
	v_pk_fma_f32 v[60:61], v[22:23], v[76:77], v[6:7]
	v_pk_mul_f32 v[76:77], v[54:55], v[72:73] op_sel_hi:[1,0]
	v_pk_mul_f32 v[54:55], v[56:57], v[72:73] op_sel_hi:[1,0]
	v_pk_fma_f32 v[56:57], v[26:27], v[76:77], v[2:3]
	v_pk_mul_f32 v[76:77], v[50:51], v[72:73] op_sel_hi:[1,0]
	v_pk_mul_f32 v[50:51], v[52:53], v[72:73] op_sel_hi:[1,0]
	v_and_b32_e32 v71, 0x3f80, v135
	v_ashrrev_i32_e32 v72, 7, v136
	v_add_u32_e32 v71, v71, v72
	s_and_b64 vcc, s[70:71], s[4:5]
	v_cndmask_b32_e32 v72, v136, v71, vcc
	v_ashrrev_i32_e32 v73, 31, v72
	v_lshlrev_b64 v[72:73], 11, v[72:73]
	v_pk_fma_f32 v[62:63], v[20:21], v[62:63], v[12:13]
	v_pk_fma_f32 v[52:53], v[30:31], v[76:77], v[14:15]
	v_lshl_add_u64 v[72:73], v[112:113], 0, v[72:73]
	v_cvt_pk_bf16_f32 v76, v64, v65
	v_cvt_pk_bf16_f32 v77, v62, v63
	v_pk_fma_f32 v[58:59], v[24:25], v[58:59], v[8:9]
	global_store_dwordx2 v[72:73], v[76:77], off
	v_cvt_pk_bf16_f32 v76, v60, v61
	v_cvt_pk_bf16_f32 v77, v58, v59
	v_pk_fma_f32 v[54:55], v[28:29], v[54:55], v[4:5]
	v_pk_fma_f32 v[50:51], v[32:33], v[50:51], v[16:17]
	global_store_dwordx2 v[72:73], v[76:77], off offset:512
	v_cvt_pk_bf16_f32 v76, v56, v57
	v_cvt_pk_bf16_f32 v77, v54, v55
	s_andn2_b64 vcc, exec, s[40:41]
	global_store_dwordx2 v[72:73], v[76:77], off offset:1024
	v_cvt_pk_bf16_f32 v76, v52, v53
	v_cvt_pk_bf16_f32 v77, v50, v51
	global_store_dwordx2 v[72:73], v[76:77], off offset:1536
	s_cbranch_vccnz .LBB0_1200
; #define LAS __attribute__((address_space(3)))
; __device__ __forceinline__ void norm_phase(const Params& P, LAS unsigned char* lds, int layer, int which, int nrows, int flags, int fprev, int fnext, const float* g2ovr, const float* xsrc, const float* gcp) {
;     ...
;             if (flags & 2) {
;                 float lg[8];
; #pragma unroll
;                 for (int e = 0; e < 8; ++e) lg[e] = 0.f;
; #pragma unroll
;                 for (int j = 0; j < 4; ++j)
; #pragma unroll
;                     for (int e = 0; e < 4; ++e) { const LAS f32x4* rr = (const LAS f32x4*)(rt + ((j * 4 + e) * 64 + lane) * 12); const f32x4 r0 = rr[0], r1 = rr[1]; const float hv = v[j][e];
;                         lg[0] += hv * r0[0]; lg[1] += hv * r0[1]; lg[2] += hv * r0[2]; lg[3] += hv * r0[3]; lg[4] += hv * r1[0]; lg[5] += hv * r1[1]; lg[6] += hv * r1[2]; lg[7] += hv * r1[3]; }
	ds_read_b128 v[76:79], v134
	ds_read_b128 v[80:83], v134 offset:16
	ds_read_b128 v[84:87], v134 offset:3072
	ds_read_b128 v[90:93], v134 offset:6160
	ds_read_b128 v[122:125], v134 offset:15376
	s_waitcnt lgkmcnt(4)
	v_fma_f32 v71, v64, v78, 0
	v_fma_f32 v140, v64, v79, 0
	s_waitcnt lgkmcnt(3)
	v_fma_f32 v141, v64, v80, 0
	v_fma_f32 v142, v64, v81, 0
	ds_read_b128 v[78:81], v134 offset:3088
	s_waitcnt lgkmcnt(3)
	v_fmac_f32_e32 v71, v65, v86
	v_fmac_f32_e32 v140, v65, v87
	ds_read_b128 v[86:89], v134 offset:6144
	v_fma_f32 v143, v64, v82, 0
	v_fma_f32 v144, v64, v83, 0
	s_waitcnt lgkmcnt(1)
	v_fmac_f32_e32 v141, v65, v78
	v_fmac_f32_e32 v142, v65, v79
	v_fmac_f32_e32 v143, v65, v80
	v_fmac_f32_e32 v144, v65, v81
	ds_read_b128 v[78:81], v134 offset:9216
	s_waitcnt lgkmcnt(1)
	v_fmac_f32_e32 v71, v62, v88
	v_fmac_f32_e32 v140, v62, v89
	v_fmac_f32_e32 v141, v62, v90
	v_fmac_f32_e32 v142, v62, v91
	ds_read_b128 v[88:91], v134 offset:9232
	v_fmac_f32_e32 v143, v62, v92
	v_fmac_f32_e32 v144, v62, v93
	s_waitcnt lgkmcnt(1)
	v_fmac_f32_e32 v71, v63, v80
	v_fmac_f32_e32 v140, v63, v81
	ds_read_b128 v[80:83], v134 offset:12288
	s_waitcnt lgkmcnt(1)
	v_fmac_f32_e32 v141, v63, v88
	v_fmac_f32_e32 v142, v63, v89
	ds_read_b128 v[92:95], v134 offset:12304
	v_fmac_f32_e32 v143, v63, v90
	v_fmac_f32_e32 v144, v63, v91
	ds_read_b128 v[88:91], v134 offset:15360
	s_waitcnt lgkmcnt(2)
	v_fmac_f32_e32 v71, v60, v82
	v_fmac_f32_e32 v140, v60, v83
	s_waitcnt lgkmcnt(1)
	v_fmac_f32_e32 v141, v60, v92
	v_fmac_f32_e32 v142, v60, v93
	v_fmac_f32_e32 v143, v60, v94
	v_fmac_f32_e32 v144, v60, v95
	s_waitcnt lgkmcnt(0)
	v_fmac_f32_e32 v71, v61, v90
	v_fmac_f32_e32 v140, v61, v91
	ds_read_b128 v[90:93], v134 offset:18432
	v_fmac_f32_e32 v141, v61, v122
	v_fmac_f32_e32 v142, v61, v123
	ds_read_b128 v[94:97], v134 offset:18448
	v_fmac_f32_e32 v143, v61, v124
	v_fmac_f32_e32 v144, v61, v125
	ds_read_b128 v[122:125], v134 offset:21504
	s_waitcnt lgkmcnt(2)
	v_fmac_f32_e32 v71, v58, v92
	v_fmac_f32_e32 v140, v58, v93
	s_waitcnt lgkmcnt(1)
	v_fmac_f32_e32 v141, v58, v94
	v_fmac_f32_e32 v142, v58, v95
	ds_read_b128 v[92:95], v134 offset:21520
	s_waitcnt lgkmcnt(1)
	v_fmac_f32_e32 v71, v59, v124
	v_fmac_f32_e32 v140, v59, v125
	ds_read_b128 v[124:127], v134 offset:24576
	v_pk_fma_f32 v[72:73], v[64:65], v[76:77], 0 op_sel_hi:[0,1,0]
	v_pk_fma_f32 v[64:65], v[64:65], v[84:85], v[72:73] op_sel:[1,0,0]
	v_fmac_f32_e32 v143, v58, v96
	v_pk_fma_f32 v[64:65], v[62:63], v[86:87], v[64:65] op_sel_hi:[0,1,1]
	v_mov_b32_e32 v62, v63
	v_pk_fma_f32 v[62:63], v[62:63], v[78:79], v[64:65] op_sel_hi:[0,1,1]
	v_fmac_f32_e32 v144, v58, v97
	v_pk_fma_f32 v[62:63], v[60:61], v[80:81], v[62:63] op_sel_hi:[0,1,1]
	s_waitcnt lgkmcnt(1)
	v_fmac_f32_e32 v141, v59, v92
	v_fmac_f32_e32 v142, v59, v93
	ds_read_b128 v[136:139], v134 offset:24592
	v_fmac_f32_e32 v143, v59, v94
	v_fmac_f32_e32 v144, v59, v95
	s_waitcnt lgkmcnt(1)
	v_fmac_f32_e32 v71, v56, v126
	v_fmac_f32_e32 v140, v56, v127
	ds_read_b128 v[92:95], v134 offset:27648
	ds_read_b128 v[126:129], v134 offset:27664
	v_pk_fma_f32 v[60:61], v[60:61], v[88:89], v[62:63] op_sel:[1,0,0]
	ds_read_b128 v[62:65], v134 offset:30736
	v_pk_fma_f32 v[60:61], v[58:59], v[90:91], v[60:61] op_sel_hi:[0,1,1]
	v_mov_b32_e32 v58, v59
	v_pk_fma_f32 v[58:59], v[58:59], v[122:123], v[60:61] op_sel_hi:[0,1,1]
	v_pk_fma_f32 v[58:59], v[56:57], v[124:125], v[58:59] op_sel_hi:[0,1,1]
	s_waitcnt lgkmcnt(2)
	v_pk_fma_f32 v[72:73], v[56:57], v[92:93], v[58:59] op_sel:[1,0,0]
	ds_read_b128 v[58:61], v134 offset:30720
	v_fmac_f32_e32 v141, v56, v136
	v_fmac_f32_e32 v142, v56, v137
	v_fmac_f32_e32 v71, v57, v94
	v_fmac_f32_e32 v140, v57, v95
	s_waitcnt lgkmcnt(2)
	v_fmac_f32_e32 v141, v57, v126
	v_fmac_f32_e32 v142, v57, v127
	ds_read_b128 v[76:79], v134 offset:33792
	s_waitcnt lgkmcnt(1)
	v_fmac_f32_e32 v71, v54, v60
	v_fmac_f32_e32 v140, v54, v61
	v_fmac_f32_e32 v141, v54, v62
	v_fmac_f32_e32 v142, v54, v63
	ds_read_b128 v[60:63], v134 offset:33808
	v_fmac_f32_e32 v143, v56, v138
	v_fmac_f32_e32 v144, v56, v139
	v_fmac_f32_e32 v143, v57, v128
	v_fmac_f32_e32 v144, v57, v129
	v_fmac_f32_e32 v143, v54, v64
	v_fmac_f32_e32 v144, v54, v65
	s_waitcnt lgkmcnt(1)
	v_fmac_f32_e32 v71, v55, v78
	v_fmac_f32_e32 v140, v55, v79
	ds_read_b128 v[78:81], v134 offset:36864
	ds_read_b128 v[82:85], v134 offset:36880
	s_waitcnt lgkmcnt(2)
	v_fmac_f32_e32 v141, v55, v60
	v_fmac_f32_e32 v142, v55, v61
	v_fmac_f32_e32 v143, v55, v62
	v_fmac_f32_e32 v144, v55, v63
	ds_read_b128 v[60:63], v134 offset:39936
	s_waitcnt lgkmcnt(2)
	v_fmac_f32_e32 v71, v52, v80
	v_fmac_f32_e32 v140, v52, v81
	v_pk_fma_f32 v[56:57], v[54:55], v[58:59], v[72:73] op_sel_hi:[0,1,1]
	v_mov_b32_e32 v54, v55
	s_waitcnt lgkmcnt(1)
	v_fmac_f32_e32 v141, v52, v82
	v_fmac_f32_e32 v142, v52, v83
	ds_read_b128 v[80:83], v134 offset:39952
	v_fmac_f32_e32 v143, v52, v84
	v_fmac_f32_e32 v144, v52, v85
	s_waitcnt lgkmcnt(1)
	v_fmac_f32_e32 v71, v53, v62
	v_fmac_f32_e32 v140, v53, v63
	ds_read_b128 v[62:65], v134 offset:43008
	ds_read_b128 v[84:87], v134 offset:43024
	ds_read_b128 v[88:91], v134 offset:46080
	ds_read_b128 v[92:95], v134 offset:46096
	v_pk_fma_f32 v[54:55], v[54:55], v[76:77], v[56:57] op_sel_hi:[0,1,1]
	v_pk_fma_f32 v[54:55], v[52:53], v[78:79], v[54:55] op_sel_hi:[0,1,1]
	v_pk_fma_f32 v[54:55], v[52:53], v[60:61], v[54:55] op_sel:[1,0,0]
	v_mov_b32_e32 v52, v51
	s_waitcnt lgkmcnt(3)
	v_pk_fma_f32 v[54:55], v[50:51], v[62:63], v[54:55] op_sel_hi:[0,1,1]
	s_waitcnt lgkmcnt(1)
	v_pk_fma_f32 v[54:55], v[52:53], v[88:89], v[54:55] op_sel_hi:[0,1,1]
	ds_bpermute_b32 v56, v0, v54
	ds_bpermute_b32 v57, v0, v55
	v_fmac_f32_e32 v141, v53, v80
	v_fmac_f32_e32 v142, v53, v81
	v_fmac_f32_e32 v143, v53, v82
	v_fmac_f32_e32 v144, v53, v83
	s_waitcnt lgkmcnt(0)
; __device__ __forceinline__ void norm_phase(const Params& P, LAS unsigned char* lds, int layer, int which, int nrows, int flags, int fprev, int fnext, const float* g2ovr, const float* xsrc, const float* gcp) {
;     ...
;                 for (int e = 0; e < 8; ++e) lg[e] = wave_sum(lg[e]);
	v_pk_add_f32 v[52:53], v[54:55], v[56:57]
	ds_bpermute_b32 v54, v66, v52
	ds_bpermute_b32 v55, v66, v53
	v_fmac_f32_e32 v71, v50, v64
	v_fmac_f32_e32 v71, v51, v90
	v_fmac_f32_e32 v140, v50, v65
	v_fmac_f32_e32 v141, v50, v84
	s_waitcnt lgkmcnt(0)
	v_pk_add_f32 v[52:53], v[52:53], v[54:55]
	v_fmac_f32_e32 v142, v50, v85
	v_fmac_f32_e32 v143, v50, v86
	v_fmac_f32_e32 v144, v50, v87
	ds_bpermute_b32 v54, v67, v52
	ds_bpermute_b32 v55, v67, v53
	ds_bpermute_b32 v50, v0, v71
	v_fmac_f32_e32 v140, v51, v91
	v_fmac_f32_e32 v141, v51, v92
	v_fmac_f32_e32 v142, v51, v93
	s_waitcnt lgkmcnt(1)
	v_pk_add_f32 v[52:53], v[52:53], v[54:55]
	s_waitcnt lgkmcnt(0)
	v_add_f32_e32 v56, v71, v50
	ds_bpermute_b32 v54, v68, v52
	ds_bpermute_b32 v55, v68, v53
	ds_bpermute_b32 v57, v66, v56
	v_fmac_f32_e32 v143, v51, v94
	v_fmac_f32_e32 v144, v51, v95
	ds_bpermute_b32 v61, v0, v142
	s_waitcnt lgkmcnt(2)
	v_pk_add_f32 v[50:51], v[52:53], v[54:55]
	s_waitcnt lgkmcnt(1)
	v_add_f32_e32 v55, v56, v57
	ds_bpermute_b32 v52, v69, v50
	ds_bpermute_b32 v53, v69, v51
	ds_bpermute_b32 v54, v0, v140
	ds_bpermute_b32 v56, v67, v55
	ds_bpermute_b32 v57, v0, v141
	s_waitcnt lgkmcnt(5)
	v_add_f32_e32 v61, v142, v61
	s_waitcnt lgkmcnt(3)
	v_pk_add_f32 v[50:51], v[50:51], v[52:53]
	s_waitcnt lgkmcnt(2)
	v_add_f32_e32 v52, v140, v54
	s_waitcnt lgkmcnt(1)
	v_add_f32_e32 v54, v55, v56
	s_waitcnt lgkmcnt(0)
	v_add_f32_e32 v55, v141, v57
	ds_bpermute_b32 v53, v66, v52
	ds_bpermute_b32 v56, v66, v55
	ds_bpermute_b32 v57, v68, v54
	ds_bpermute_b32 v62, v66, v61
	s_waitcnt lgkmcnt(3)
	v_add_f32_e32 v53, v52, v53
	s_waitcnt lgkmcnt(2)
	v_add_f32_e32 v55, v55, v56
	ds_bpermute_b32 v58, v67, v53
	ds_bpermute_b32 v56, v67, v55
	s_waitcnt lgkmcnt(3)
	v_add_f32_e32 v54, v54, v57
	ds_bpermute_b32 v59, v69, v54
	s_waitcnt lgkmcnt(3)
	v_add_f32_e32 v61, v61, v62
	s_waitcnt lgkmcnt(2)
	v_add_f32_e32 v57, v53, v58
	s_waitcnt lgkmcnt(1)
	v_add_f32_e32 v55, v55, v56
	ds_bpermute_b32 v58, v68, v57
	ds_bpermute_b32 v56, v68, v55
	s_waitcnt lgkmcnt(2)
	v_add_f32_e32 v54, v54, v59
	ds_bpermute_b32 v62, v67, v61
	ds_bpermute_b32 v52, v70, v50
	s_waitcnt lgkmcnt(3)
	v_add_f32_e32 v57, v57, v58
	s_waitcnt lgkmcnt(2)
	v_add_f32_e32 v59, v55, v56
	ds_bpermute_b32 v58, v69, v57
	ds_bpermute_b32 v60, v69, v59
	s_waitcnt lgkmcnt(3)
	v_add_f32_e32 v61, v61, v62
	ds_bpermute_b32 v62, v68, v61
	ds_bpermute_b32 v53, v70, v51
	s_waitcnt lgkmcnt(3)
	v_add_f32_e32 v56, v57, v58
	s_waitcnt lgkmcnt(2)
	v_add_f32_e32 v58, v59, v60
	ds_bpermute_b32 v60, v0, v143
	ds_bpermute_b32 v0, v0, v144
	s_waitcnt lgkmcnt(3)
	v_add_f32_e32 v61, v61, v62
	ds_bpermute_b32 v62, v69, v61
	ds_bpermute_b32 v55, v70, v54
	s_waitcnt lgkmcnt(3)
	v_add_f32_e32 v60, v143, v60
	s_waitcnt lgkmcnt(2)
	v_add_f32_e32 v0, v144, v0
	ds_bpermute_b32 v63, v66, v60
	ds_bpermute_b32 v64, v66, v0
	ds_bpermute_b32 v57, v70, v56
	ds_bpermute_b32 v59, v70, v58
	s_waitcnt lgkmcnt(3)
	v_add_f32_e32 v60, v60, v63
	s_waitcnt lgkmcnt(2)
	v_add_f32_e32 v0, v0, v64
	ds_bpermute_b32 v63, v67, v60
	ds_bpermute_b32 v64, v67, v0
	s_waitcnt lgkmcnt(1)
	v_add_f32_e32 v60, v60, v63
	s_waitcnt lgkmcnt(0)
	v_add_f32_e32 v0, v0, v64
	ds_bpermute_b32 v63, v68, v60
	ds_bpermute_b32 v64, v68, v0
	s_waitcnt lgkmcnt(1)
	v_add_f32_e32 v63, v60, v63
	s_waitcnt lgkmcnt(0)
	v_add_f32_e32 v64, v0, v64
	ds_bpermute_b32 v65, v69, v63
	ds_bpermute_b32 v66, v69, v64
	v_add_f32_e32 v0, v61, v62
	ds_bpermute_b32 v60, v70, v0
	s_waitcnt lgkmcnt(2)
	v_add_f32_e32 v61, v63, v65
	s_waitcnt lgkmcnt(1)
	v_add_f32_e32 v63, v64, v66
	ds_bpermute_b32 v62, v70, v61
	ds_bpermute_b32 v64, v70, v63
	s_and_saveexec_b64 s[62:63], s[0:1]
	s_cbranch_execz .LBB0_1199
; __device__ __forceinline__ void norm_phase(const Params& P, LAS unsigned char* lds, int layer, int which, int nrows, int flags, int fprev, int fnext, const float* g2ovr, const float* xsrc, const float* gcp) {
;     ...
;                 int e0 = 0; float v0 = lg[0];
; #pragma unroll
;                 for (int e = 1; e < 8; ++e) if (lg[e] > v0) { v0 = lg[e]; e0 = e; }
;                 int e1 = -1; float v1 = -3.0e38f;
; #pragma unroll
;                 for (int e = 0; e < 8; ++e) if (e != e0 && lg[e] > v1) { v1 = lg[e]; e1 = e; }
;                 if (lane == 0) {
;                     const int rho = ((r - gw) / ngw) * NWAVE + wave;
;                     etab[2 * rho] = e0; etab[2 * rho + 1] = e1;
;                     const float ex = __expf(v1 - v0), w0 = 1.f / (1.f + ex);
;                     ((float2*)(ws + O_RW))[r] = make_float2(w0, ex * w0);
;                 }
	v_pk_add_f32 v[50:51], v[50:51], v[52:53]
	v_add_f32_e32 v54, v54, v55
	v_cmp_gt_f32_e32 vcc, v51, v50
	v_add_f32_e32 v56, v56, v57
	v_add_f32_e32 v58, v58, v59
	v_cndmask_b32_e32 v52, v50, v51, vcc
	v_cmp_gt_f32_e64 s[4:5], v54, v52
	s_waitcnt lgkmcnt(2)
	v_add_f32_e32 v0, v0, v60
	s_waitcnt lgkmcnt(1)
	v_add_f32_e32 v61, v61, v62
	v_cndmask_b32_e64 v52, v52, v54, s[4:5]
	v_cmp_gt_f32_e64 s[6:7], v56, v52
	s_waitcnt lgkmcnt(0)
	v_add_f32_e32 v63, v63, v64
	s_mov_b32 s2, 0xff61b1e6
	v_cndmask_b32_e64 v52, v52, v56, s[6:7]
	v_cmp_gt_f32_e64 s[8:9], v58, v52
	v_cmp_nlt_f32_e64 s[18:19], s2, v50
	v_mov_b32_e32 v53, 0xff61b1e6
	v_cndmask_b32_e64 v52, v52, v58, s[8:9]
	v_cmp_gt_f32_e64 s[12:13], v0, v52
	s_abs_i32 s3, s66
	s_ashr_i32 s2, s66, 31
	v_cndmask_b32_e64 v52, v52, v0, s[12:13]
	v_cmp_gt_f32_e64 s[14:15], v61, v52
	s_xor_b32 s2, s2, s75
	s_nop 0
	v_cndmask_b32_e64 v55, v52, v61, s[14:15]
	v_cndmask_b32_e64 v52, 0, 1, vcc
	v_cndmask_b32_e64 v52, v52, 2, s[4:5]
	v_cndmask_b32_e64 v52, v52, 3, s[6:7]
	v_cndmask_b32_e64 v52, v52, 4, s[8:9]
	v_cndmask_b32_e64 v52, v52, 5, s[12:13]
	v_cndmask_b32_e64 v52, v52, 6, s[14:15]
	v_cmp_ngt_f32_e32 vcc, v63, v55
	s_and_b64 s[20:21], s[14:15], vcc
	s_nop 0
	v_cndmask_b32_e32 v52, 7, v52, vcc
	v_cmp_eq_u32_e64 s[16:17], 0, v52
	s_or_b64 s[16:17], s[16:17], s[18:19]
	v_cmp_ne_u32_e64 s[14:15], 1, v52
	v_cndmask_b32_e64 v50, v50, v53, s[16:17]
	v_cmp_gt_f32_e64 s[18:19], v51, v50
	s_and_b64 s[14:15], s[14:15], s[18:19]
	v_cndmask_b32_e64 v50, v50, v51, s[14:15]
	v_cmp_ne_u32_e64 s[12:13], 2, v52
	v_cmp_gt_f32_e64 s[18:19], v54, v50
	s_and_b64 s[12:13], s[12:13], s[18:19]
	v_cndmask_b32_e64 v50, v50, v54, s[12:13]
	v_cmp_ne_u32_e64 s[8:9], 3, v52
	v_cmp_gt_f32_e64 s[18:19], v56, v50
	s_and_b64 s[8:9], s[8:9], s[18:19]
	v_cndmask_b32_e64 v50, v50, v56, s[8:9]
	v_cmp_ne_u32_e64 s[6:7], 4, v52
	v_cmp_gt_f32_e64 s[18:19], v58, v50
	s_and_b64 s[6:7], s[6:7], s[18:19]
	v_cndmask_b32_e64 v50, v50, v58, s[6:7]
	v_cmp_ne_u32_e64 s[4:5], 5, v52
	v_cmp_gt_f32_e64 s[18:19], v0, v50
	s_and_b64 s[4:5], s[4:5], s[18:19]
	v_cndmask_b32_e64 v0, v50, v0, s[4:5]
	v_cndmask_b32_e64 v50, 0, -1, s[16:17]
	v_cndmask_b32_e64 v50, v50, 1, s[14:15]
	v_cmp_ngt_f32_e64 s[18:19], v61, v0
	v_cndmask_b32_e64 v50, v50, 2, s[12:13]
	s_or_b64 s[18:19], s[20:21], s[18:19]
	v_cndmask_b32_e64 v50, v50, 3, s[8:9]
	v_cndmask_b32_e64 v0, v61, v0, s[18:19]
	v_cndmask_b32_e64 v50, v50, 4, s[6:7]
	v_cmp_gt_f32_e64 s[20:21], v63, v0
	v_cndmask_b32_e64 v50, v50, 5, s[4:5]
	s_and_b64 s[20:21], vcc, s[20:21]
	v_cndmask_b32_e64 v50, 6, v50, s[18:19]
	v_cndmask_b32_e64 v0, v0, v63, s[20:21]
	v_cndmask_b32_e64 v53, v50, 7, s[20:21]
	v_cndmask_b32_e32 v50, v63, v55, vcc
	s_mul_hi_u32 s4, s3, s67
	s_mul_i32 s5, s4, s30
	v_sub_f32_e32 v0, v0, v50
	s_sub_i32 s3, s3, s5
	v_mul_f32_e32 v0, 0x3fb8aa3b, v0
	s_add_i32 s5, s4, 1
	s_sub_i32 s6, s3, s30
	v_exp_f32_e32 v0, v0
	s_cmp_ge_u32 s3, s30
	s_cselect_b32 s4, s5, s4
	s_cselect_b32 s3, s6, s3
	s_add_i32 s5, s4, 1
	s_cmp_ge_u32 s3, s30
	v_add_f32_e32 v50, 1.0, v0
	s_cselect_b32 s3, s5, s4
	v_div_scale_f32 v51, s[4:5], v50, v50, 1.0
	v_rcp_f32_e32 v54, v51
	s_xor_b32 s3, s3, s2
	s_sub_i32 s2, s3, s2
	v_lshl_add_u32 v55, s2, 6, v101
	ds_write_b64 v55, v[52:53] offset:49152
	v_fma_f32 v52, -v51, v54, 1.0
	v_fmac_f32_e32 v54, v52, v54
	v_div_scale_f32 v52, vcc, 1.0, v50, 1.0
	v_mul_f32_e32 v53, v52, v54
	v_fma_f32 v55, -v51, v53, v52
	v_fmac_f32_e32 v53, v55, v54
	v_fma_f32 v51, -v51, v53, v52
	v_div_fmas_f32 v51, v51, v54, v53
	v_lshl_add_u64 v[52:53], s[28:29], 0, v[118:119]
	v_div_fixup_f32 v50, v51, v50, 1.0
	v_add_co_u32_e32 v52, vcc, 0x119000, v52
	v_mul_f32_e32 v51, v0, v50
	s_nop 0
	v_addc_co_u32_e32 v53, vcc, 0, v53, vcc
	global_store_dwordx2 v[52:53], v[50:51], off
	s_branch .LBB0_1199

; __global__ void __launch_bounds__(NTHR, 2) mega_fwd(Params P) {
	.amdhsa_kernel _Z8mega_fwd6Params
		.amdhsa_group_segment_fixed_size 0
		.amdhsa_private_segment_fixed_size 0
		.amdhsa_kernarg_size 448
		.amdhsa_user_sgpr_count 2
		.amdhsa_user_sgpr_dispatch_ptr 0
		.amdhsa_user_sgpr_queue_ptr 0
		.amdhsa_user_sgpr_kernarg_segment_ptr 1
		.amdhsa_user_sgpr_dispatch_id 0
		.amdhsa_user_sgpr_kernarg_preload_length 0
		.amdhsa_user_sgpr_kernarg_preload_offset 0
		.amdhsa_user_sgpr_private_segment_size 0
		.amdhsa_uses_dynamic_stack 0
		.amdhsa_enable_private_segment 0
		.amdhsa_system_sgpr_workgroup_id_x 1
		.amdhsa_system_sgpr_workgroup_id_y 0
		.amdhsa_system_sgpr_workgroup_id_z 0
		.amdhsa_system_sgpr_workgroup_info 0
		.amdhsa_system_vgpr_workitem_id 2
		.amdhsa_next_free_vgpr 256
		.amdhsa_next_free_sgpr 102
		.amdhsa_accum_offset 256
		.amdhsa_reserve_vcc 1
		.amdhsa_float_round_mode_32 0
		.amdhsa_float_round_mode_16_64 0
		.amdhsa_float_denorm_mode_32 3
		.amdhsa_float_denorm_mode_16_64 3
		.amdhsa_dx10_clamp 1
		.amdhsa_ieee_mode 1
		.amdhsa_fp16_overflow 0
		.amdhsa_tg_split 0
		.amdhsa_exception_fp_ieee_invalid_op 0
		.amdhsa_exception_fp_denorm_src 0
		.amdhsa_exception_fp_ieee_div_zero 0
		.amdhsa_exception_fp_ieee_overflow 0
		.amdhsa_exception_fp_ieee_underflow 0
		.amdhsa_exception_fp_ieee_inexact 0
		.amdhsa_exception_int_div_zero 0
	.end_amdhsa_kernel

; __global__ void __launch_bounds__(NTHR, 2) mega_fwd(Params P) {
amdhsa.kernels:
  - .agpr_count:     0
    .args:
      - .offset:         0
        .size:           192
        .value_kind:     by_value
      - .offset:         192
        .size:           4
        .value_kind:     hidden_block_count_x
      - .offset:         196
        .size:           4
        .value_kind:     hidden_block_count_y
      - .offset:         200
        .size:           4
        .value_kind:     hidden_block_count_z
      - .offset:         204
        .size:           2
        .value_kind:     hidden_group_size_x
      - .offset:         206
        .size:           2
        .value_kind:     hidden_group_size_y
      - .offset:         208
        .size:           2
        .value_kind:     hidden_group_size_z
      - .offset:         210
        .size:           2
        .value_kind:     hidden_remainder_x
      - .offset:         212
        .size:           2
        .value_kind:     hidden_remainder_y
      - .offset:         214
        .size:           2
        .value_kind:     hidden_remainder_z
      - .offset:         232
        .size:           8
        .value_kind:     hidden_global_offset_x
      - .offset:         240
        .size:           8
        .value_kind:     hidden_global_offset_y
      - .offset:         248
        .size:           8
        .value_kind:     hidden_global_offset_z
      - .offset:         256
        .size:           2
        .value_kind:     hidden_grid_dims
      - .offset:         280
        .size:           8
        .value_kind:     hidden_multigrid_sync_arg
      - .offset:         312
        .size:           4
        .value_kind:     hidden_dynamic_lds_size
    .group_segment_fixed_size: 0
    .kernarg_segment_align: 8
    .kernarg_segment_size: 448
    .language:       OpenCL C
    .language_version:
      - 2
      - 0
    .max_flat_workgroup_size: 512
    .name:           _Z8mega_fwd6Params
    .private_segment_fixed_size: 0
    .sgpr_count:     108
    .sgpr_spill_count: 540
    .symbol:         _Z8mega_fwd6Params.kd
    .uniform_work_group_size: 1
    .uses_dynamic_stack: false
    .vgpr_count:     256
    .vgpr_spill_count: 0
    .wavefront_size: 64
